# attention: exact skip of fully window-masked key tiles, skip mask on fully visible tiles, query-half remap so SIMD partner waves differ
# speedup vs baseline: 1.0131x; 1.0101x over previous
.LBB0_804:
	s_and_b32 s10, s6, 1
	s_lshl_b32 s7, s10, 2
	s_ashr_i32 s9, s8, 7
	s_add_i32 s12, s9, s7
	s_lshl_b32 s14, s12, 6
	s_ashr_i32 s15, s14, 31
	v_and_b32_e32 v16, 31, v17
	s_lshr_b32 s7, s8, 2
	s_xor_b32 s7, s7, s8
	s_and_b32 s7, s7, 64
	s_lshl_b64 s[38:39], s[14:15], 1
	v_bfe_u32 v18, v17, 5, 1
	v_or_b32_e32 v162, s7, v16
	s_add_u32 s14, s92, s38
	v_lshl_add_u64 v[2:3], s[2:3], 0, v[162:163]
	s_addc_u32 s15, s93, s39
	v_lshlrev_b32_e32 v0, 4, v18
	s_waitcnt lgkmcnt(0)
	v_mov_b32_e32 v1, v163
	v_lshl_add_u64 v[4:5], s[14:15], 0, v[0:1]
	v_lshlrev_b64 v[2:3], 10, v[2:3]
	v_lshl_add_u64 v[2:3], v[4:5], 0, v[2:3]
	s_mov_b32 s9, 0x8000
	global_load_dwordx4 v[96:99], v[2:3], off
	global_load_dwordx4 v[100:103], v[2:3], off offset:32
	global_load_dwordx4 v[104:107], v[2:3], off offset:64
	global_load_dwordx4 v[108:111], v[2:3], off offset:96
	v_add_co_u32_e32 v2, vcc, s9, v2
	s_ashr_i32 s13, s12, 31
	s_nop 0
	v_addc_co_u32_e32 v3, vcc, 0, v3, vcc
	s_lshl_b64 s[12:13], s[12:13], 2
	global_load_dwordx4 v[112:115], v[2:3], off
	global_load_dwordx4 v[116:119], v[2:3], off offset:32
	global_load_dwordx4 v[120:123], v[2:3], off offset:64
	global_load_dwordx4 v[124:127], v[2:3], off offset:96
	s_add_u32 s12, s4, s12
	s_addc_u32 s13, s5, s13
	global_load_dword v1, v163, s[12:13]
	s_cmp_eq_u32 s11, 0
	s_cselect_b64 s[12:13], -1, 0
	v_cndmask_b32_e64 v2, 0, 1, s[12:13]
	s_and_b64 s[12:13], s[40:41], exec
	v_readfirstlane_b32 s9, v2
	s_cselect_b32 s9, 3, s9
	s_lshl_b32 s13, s9, 7
	s_add_i32 s12, s13, 0xffffff80
	v_ashrrev_i32_e32 v2, 3, v17
	s_andn2_b64 vcc, exec, s[42:43]
	s_mov_b64 s[48:49], -1
	s_cbranch_vccnz .LBB0_806
	s_ashr_i32 s37, s36, 31
	s_lshl_b64 s[14:15], s[36:37], 12
	s_lshl_b32 s16, s11, 7
	v_add_u32_e32 v4, s12, v2
	v_ashrrev_i32_e32 v5, 31, v4
	s_or_b32 s14, s14, s16
	v_lshl_add_u64 v[4:5], s[14:15], 0, v[4:5]
	s_mov_b64 s[48:49], 0

.LBB0_816:
	s_cmp_eq_u32 s9, 0
	s_cbranch_scc1 .Latt_sk0
	s_cmp_eq_u32 s9, 2
	s_cbranch_scc0 .Latt_noskip
	s_cmp_eq_u32 s7, 0
	s_cbranch_scc0 .Latt_noskip
	s_cmp_ge_u32 s13, 64
	s_cbranch_scc1 .Latt_skipkt
	s_branch .Latt_noskip
.Latt_sk0:
	s_cmp_eq_u32 s7, 64
	s_cbranch_scc0 .Latt_noskip
	s_cmp_lt_u32 s13, 64
	s_cbranch_scc1 .Latt_skipkt

.LBB0_820:
	s_andn2_b64 vcc, exec, s[50:51]
	s_cbranch_vccnz .LBB0_822
	s_and_b64 vcc, exec, s[36:37]
	s_cbranch_vccz .Latt_mk2
	s_cmp_eq_u32 s7, 0
	s_cbranch_scc0 .Latt_domask
	s_cmp_ge_u32 s13, 64
	s_cbranch_scc1 .LBB0_822
	s_branch .Latt_domask

.Latt_domask:
	v_add_u32_e32 v164, s13, v183
	v_sub_u32_e32 v165, v162, v164
	v_add_u32_e32 v166, 32, v165
	s_and_b64 vcc, exec, s[36:37]
	s_cbranch_vccz .Latt_m2
	v_cmp_lt_i32_e64 s[20:21], 0, v165
	v_cmp_lt_i32_e64 s[22:23], 1, v165
	v_cmp_lt_i32_e64 s[24:25], 2, v165
	v_cndmask_b32_e64 v80, v80, v205, s[20:21]
	v_cmp_lt_i32_e64 s[20:21], 3, v165
	v_cndmask_b32_e64 v81, v81, v205, s[22:23]
	v_cmp_lt_i32_e64 s[22:23], 8, v165
	v_cndmask_b32_e64 v82, v82, v205, s[24:25]
	v_cmp_lt_i32_e64 s[24:25], 9, v165
	v_cndmask_b32_e64 v83, v83, v205, s[20:21]
	v_cmp_lt_i32_e64 s[20:21], 10, v165
	v_cndmask_b32_e64 v84, v84, v205, s[22:23]
	v_cmp_lt_i32_e64 s[22:23], 11, v165
	v_cndmask_b32_e64 v85, v85, v205, s[24:25]
	v_cmp_lt_i32_e64 s[24:25], 16, v165
	v_cndmask_b32_e64 v86, v86, v205, s[20:21]
	v_cmp_lt_i32_e64 s[20:21], 17, v165
	v_cndmask_b32_e64 v87, v87, v205, s[22:23]
	v_cmp_lt_i32_e64 s[22:23], 18, v165
	v_cndmask_b32_e64 v88, v88, v205, s[24:25]
	v_cmp_lt_i32_e64 s[24:25], 19, v165
	v_cndmask_b32_e64 v89, v89, v205, s[20:21]
	v_cmp_lt_i32_e64 s[20:21], 24, v165
	v_cndmask_b32_e64 v90, v90, v205, s[22:23]
	v_cmp_lt_i32_e64 s[22:23], 25, v165
	v_cndmask_b32_e64 v91, v91, v205, s[24:25]
	v_cmp_lt_i32_e64 s[24:25], 26, v165
	v_cndmask_b32_e64 v92, v92, v205, s[20:21]
	v_cmp_lt_i32_e64 s[20:21], 27, v165
	v_cndmask_b32_e64 v93, v93, v205, s[22:23]
	v_cmp_lt_i32_e64 s[22:23], 0, v166
	v_cndmask_b32_e64 v94, v94, v205, s[24:25]
	v_cmp_lt_i32_e64 s[24:25], 1, v166
	v_cndmask_b32_e64 v95, v95, v205, s[20:21]
	v_cmp_lt_i32_e64 s[20:21], 2, v166
	v_cndmask_b32_e64 v64, v64, v205, s[22:23]
	v_cmp_lt_i32_e64 s[22:23], 3, v166
	v_cndmask_b32_e64 v65, v65, v205, s[24:25]
	v_cmp_lt_i32_e64 s[24:25], 8, v166
	v_cndmask_b32_e64 v66, v66, v205, s[20:21]
	v_cmp_lt_i32_e64 s[20:21], 9, v166
	v_cndmask_b32_e64 v67, v67, v205, s[22:23]
	v_cmp_lt_i32_e64 s[22:23], 10, v166
	v_cndmask_b32_e64 v68, v68, v205, s[24:25]
	v_cmp_lt_i32_e64 s[24:25], 11, v166
	v_cndmask_b32_e64 v69, v69, v205, s[20:21]
	v_cmp_lt_i32_e64 s[20:21], 16, v166
	v_cndmask_b32_e64 v70, v70, v205, s[22:23]
	v_cmp_lt_i32_e64 s[22:23], 17, v166
	v_cndmask_b32_e64 v71, v71, v205, s[24:25]
	v_cmp_lt_i32_e64 s[24:25], 18, v166
	v_cndmask_b32_e64 v72, v72, v205, s[20:21]
	v_cmp_lt_i32_e64 s[20:21], 19, v166
	v_cndmask_b32_e64 v73, v73, v205, s[22:23]
	v_cmp_lt_i32_e64 s[22:23], 24, v166
	v_cndmask_b32_e64 v74, v74, v205, s[24:25]
	v_cmp_lt_i32_e64 s[24:25], 25, v166
	v_cndmask_b32_e64 v75, v75, v205, s[20:21]
	v_cmp_lt_i32_e64 s[20:21], 26, v166
	v_cndmask_b32_e64 v76, v76, v205, s[22:23]
	v_cmp_lt_i32_e64 s[22:23], 27, v166
	v_cndmask_b32_e64 v77, v77, v205, s[24:25]
	v_cndmask_b32_e64 v78, v78, v205, s[20:21]
	v_cndmask_b32_e64 v79, v79, v205, s[22:23]
	s_branch .LBB0_822

.Latt_pv:
	s_setprio 1
	s_waitcnt lgkmcnt(3)
	v_mfma_f32_32x32x16_bf16 v[32:47], v[72:75], v[80:83], v[32:47]
	v_mfma_f32_32x32x16_bf16 v[16:31], v[72:75], v[64:67], v[16:31]
	s_waitcnt lgkmcnt(2)
	v_mfma_f32_32x32x16_bf16 v[48:63], v[76:79], v[80:83], v[48:63]
	v_mfma_f32_32x32x16_bf16 v[0:15], v[76:79], v[64:67], v[0:15]
	s_waitcnt lgkmcnt(1)
	v_mfma_f32_32x32x16_bf16 v[32:47], v[168:171], v[84:87], v[32:47]
	v_mfma_f32_32x32x16_bf16 v[16:31], v[168:171], v[68:71], v[16:31]
	s_waitcnt lgkmcnt(0)
	v_mfma_f32_32x32x16_bf16 v[48:63], v[92:95], v[84:87], v[48:63]
	v_mfma_f32_32x32x16_bf16 v[0:15], v[92:95], v[68:71], v[0:15]
	s_setprio 0
	s_branch .Latt_tail
.Latt_skipkt:
	v_mov_b32_e32 v190, v159
	v_mov_b32_e32 v191, v158
.Latt_tail:
	s_add_i32 s13, s13, 32
	v_add_u32_e32 v188, 64, v188
	s_cmpk_eq_i32 s13, 0x80
	v_add_u32_e32 v189, 0x1200, v189
	s_cbranch_scc1 .LBB0_824
	v_mov_b32_e32 v158, v191
	v_mov_b32_e32 v159, v190
	s_branch .LBB0_816
